# P1: workgroups on the upper half of each XCD's token-tile set start the phase half a unit (~15us) later, so the two groups' epilogue store bursts alternate
# speedup vs baseline: 1.0217x; 1.0017x over previous
;     __device__ bool next(int i, Unit& u) const { if (!so.next(i >> 1, u)) return false; u.sel = i & 1; return true; }
;     __host__ __device__ bool next(int i, Unit& u) const {
;         const long L = (long)i * G + c; if (L >= nwg) return false;
;         int wgid = (int)L; { const int q = nwg / NXCD, r = nwg % NXCD, xcd = wgid % NXCD, off = wgid / NXCD; wgid = (xcd < r ? xcd * (q + 1) : r * (q + 1) + (xcd - r) * q) + off; }
;         const int nig = WGM * nN, gid = wgid / nig, fm = gid * WGM, gsz = (nM - fm) < WGM ? (nM - fm) : WGM;
;         u.pm = fm + ((wgid % nig) % gsz); u.pn = (wgid % nig) / gsz; u.sel = 0; return true;
; __global__ void __launch_bounds__(NTHREADS, 2) fwd_megakernel(Params p) {
;     ...
;     { pg8::Gemm g{(const wb*)(ws + WS_R0), (const wb*)(ws + W_IN), MP, N_IN, DM, nullptr, nullptr}; pg8::StaticOrder S; S.init(MP, N_IN, G, bx);
;       pg8::EpiInProj E{(wb*)(ws + WS_R1), (wb*)(ws + WS_R2), (wb*)(ws + WS_R3), (wb*)(ws + WS_R4), (wb*)(ws + WS_CQ), (wb*)(ws + WS_CKV), (wb*)p.out, (wb*)(ws + WS_KPE), (float*)(ws + PART_Q), (float*)(ws + PART_KV), p.b_gate, ropecs};
;       pg8::gemm_phase<pg8::EpiInProj, pg8::StaticOrder, true, true>(lds, g, S, E); }
.LBB0_192:
	s_or_b64 exec, exec, s[0:1]
	s_bitcmp1_b32 s2, 5
	s_cbranch_scc0 .List1_done
	s_sleep 127
	s_sleep 127
	s_sleep 127
	s_sleep 127
.List1_done:
	v_readfirstlane_b32 s99, v201
	s_nop 3
	s_bfe_u32 s99, s99, 0x20006
	s_cmp_lg_u32 s99, 0
	s_cselect_b32 s99, 3, 0
	v_mov_b32_e32 v1, v201
	s_cmpk_lt_i32 s2, 0x1b1b
	s_waitcnt lgkmcnt(0)
	s_barrier
	s_movk_i32 s0, 0x400
	v_readfirstlane_b32 s3, v1
	s_cselect_b64 s[4:5], -1, 0
	s_cmpk_gt_i32 s2, 0x1b1a
	s_cbranch_scc1 .LBB0_198
	s_ashr_i32 s1, s2, 31
	s_lshr_b32 s1, s1, 29
	s_add_i32 s1, s2, s1
	s_and_b32 s6, s1, -8
	s_sub_i32 s8, s2, s6
	s_cmp_gt_i32 s8, 2
	s_cbranch_scc0 .LBB0_195
	s_mul_i32 s6, s8, 0x363
	s_add_i32 s9, s6, 3
	s_cbranch_execz .LBB0_196
	s_branch .LBB0_197
